# attn2: vmcnt(0) after fresh K/V tile loads -> counted vmcnt(2) on the issuing path
# speedup vs baseline: 1.0044x; 1.0044x over previous
;     ...
;         auto gload = [&](u32x4 (&rg)[NJ], float& ckr, int t) {
; #pragma unroll
;             for (int j = 0; j < NJ; ++j) rg[j] = *(const u32x4*)(src[j] + (size_t)t * step[j]);
;             if (MODE == 1 && tid < 64) ckr = ckp[t * 64 + tid];
;         };
;     ...
;         auto stepf = [&](f32x16 (&s_cur)[2], const float mi_cur, f32x16 (&s_nxt)[2], float& mi_nxt, u32x4 (&rg_ld)[NJ], float& ck_ld, const u32x4 (&rg_st)[NJ], const float ck_st, int kk) {
;             const int kt = j0 + kk;
;             if (DEEP) { if (kk + 3 < ntl) gload(rg_ld, ck_ld, kt + 3); } else { if (kk + 2 < ntl) gload(rg_ld, ck_ld, kt + 2); }
;             if (MODE == 2 && kk + 2 < ntl) wnext2 = mrow[kt + 2];
;             if (kk + 1 < ntl && (kt + 1) * 64 <= qw0 + 31) qk(s_nxt, mi_nxt, (kk + 1) % 3);
;             if (kt * 64 <= qw0 + 31) softmax_pv(s_cur, mi_cur, kt, kk % 3);
;             if (MODE == 2) { wcur = wnext; wnext = wnext2; }
;             if (kk + 2 < ntl) lstore(rg_st, ck_st, (kk + 2) % 3);
;             __syncthreads();
.LBB0_3620:
	s_cmp_ge_i32 s52, s40
	s_waitcnt lgkmcnt(0)
	s_barrier
	s_cbranch_scc1 .LBB0_3631
	s_cmp_ge_i32 s45, s40
	s_cbranch_scc1 .LBB0_3623
	v_lshl_add_u64 v[4:5], s[42:43], 0, v[186:187]
	v_add_co_u32_e32 v4, vcc, 0x73c0000, v4
	v_lshl_add_u64 v[6:7], s[42:43], 0, v[184:185]
	s_nop 0
	v_addc_co_u32_e32 v5, vcc, 0, v5, vcc
	v_add_co_u32_e32 v6, vcc, 0x15200000, v6
	s_nop 1
	v_addc_co_u32_e32 v7, vcc, 0, v7, vcc
	global_load_dwordx4 v[134:137], v[4:5], off offset:2048
	global_load_dwordx4 v[138:141], v[6:7], off offset:512
	s_waitcnt vmcnt(2)
	s_branch .Lmy_a2_w3join

;     ...
;         auto stepf = [&](f32x16 (&s_cur)[2], const float mi_cur, f32x16 (&s_nxt)[2], float& mi_nxt, u32x4 (&rg_ld)[NJ], float& ck_ld, const u32x4 (&rg_st)[NJ], const float ck_st, int kk) {
;             const int kt = j0 + kk;
;             if (DEEP) { if (kk + 3 < ntl) gload(rg_ld, ck_ld, kt + 3); } else { if (kk + 2 < ntl) gload(rg_ld, ck_ld, kt + 2); }
;             if (MODE == 2 && kk + 2 < ntl) wnext2 = mrow[kt + 2];
;             if (kk + 1 < ntl && (kt + 1) * 64 <= qw0 + 31) qk(s_nxt, mi_nxt, (kk + 1) % 3);
;             if (kt * 64 <= qw0 + 31) softmax_pv(s_cur, mi_cur, kt, kk % 3);
;             if (MODE == 2) { wcur = wnext; wnext = wnext2; }
;             if (kk + 2 < ntl) lstore(rg_st, ck_st, (kk + 2) % 3);
.Lmy_a2_w3join:
	v_cndmask_b32_e64 v1, 0, 1, s[6:7]
	v_cmp_ne_u32_e64 s[4:5], 1, v1
	s_andn2_b64 vcc, exec, s[6:7]
	v_mov_b64_e32 v[114:115], v[190:191]
	s_cbranch_vccnz .LBB0_3625
	v_lshl_add_u64 v[4:5], s[42:43], 0, v[180:181]
	v_add_co_u32_e32 v4, vcc, 0x1d200000, v4
	s_nop 1
	v_addc_co_u32_e32 v5, vcc, 0, v5, vcc
	global_load_dwordx2 v[114:115], v[4:5], off offset:24
